# speedup vs baseline: 1.0628x; 1.0018x over previous
; #define STAGE(P, q) do { GLDS16(q[0], (unsigned char*)(P) + wid * 1024); GLDS16(q[1], (unsigned char*)(P) + wid * 1024 + 8192); \
;     q[0] += 128; q[1] += 128; asm volatile("" : "+v"(q[0]), "+v"(q[1])); } while (0)
; #define LDA(dst, b, h) _Pragma("unroll") for (int m = 0; m < 4; ++m) _Pragma("unroll") for (int k = 0; k < 2; ++k) \
;     dst[m][k] = *(const bf16x8*)((const unsigned char*)SA(b, h) + lds_byte1(wr * 64 + m * 16 + fr, k * 32 + fq * 8))
; #define LDB(dst, b, h) _Pragma("unroll") for (int n = 0; n < 2; ++n) _Pragma("unroll") for (int k = 0; k < 2; ++k) \
;     dst[n][k] = *(const bf16x8*)((const unsigned char*)SB(b, h) + lds_byte1(wc * 32 + n * 16 + fr, k * 32 + fq * 8))
; #define MMA(ai, bj, At_, Bt_) do { __builtin_amdgcn_s_setprio(1); \
;     _Pragma("unroll") for (int m = 0; m < 4; ++m) _Pragma("unroll") for (int n = 0; n < 2; ++n) _Pragma("unroll") for (int k = 0; k < 2; ++k) \
;       acc[ai][bj][m][n] = mfma16(At_[m][k], Bt_[n][k], acc[ai][bj][m][n]); \
;     __builtin_amdgcn_s_setprio(0); } while (0)
; #define WAIT_V(n) asm volatile("s_waitcnt vmcnt(" #n ")" ::: "memory")
; #define WAIT_L(n) asm volatile("s_waitcnt lgkmcnt(" #n ")" ::: "memory")
; #define BAR __builtin_amdgcn_s_barrier()
; DEV void gemm_tile(const u16* __restrict__ A, const u16* __restrict__ Bt, u16* __restrict__ C, int N, int K,
;                    int brow, int bcol, unsigned char* smem, int epi, const GateEpi& ge) {
;     ...
;   STAGE(SB(0, 0), qB0); STAGE(SA(0, 0), qA0);
;   STAGE(SB(0, 1), qB1); STAGE(SA(0, 1), qA1);
;   if (wr == 1) BAR;
;   WAIT_V(4); BAR;
;   STAGE(SB(1, 0), qB0); STAGE(SA(1, 0), qA0); STAGE(SB(1, 1), qB1);
;     ...
;   { LDB(B0, 0, 0); LDA(At, 0, 0); STAGE(SA(1, 1), qA1);
;     BAR; WAIT_L(0); MMA(0, 0, At, B0); BAR;
;     LDB(B1, 0, 1); BAR; WAIT_L(0); MMA(0, 1, At, B1); BAR;
;     LDA(At, 0, 1); WAIT_V(4); BAR; WAIT_L(0); MMA(1, 0, At, B0); MMA(1, 1, At, B1); BAR; }
;   { LDB(B0, 1, 0); LDA(At, 1, 0); WAIT_V(2); BAR; WAIT_L(0); MMA(0, 0, At, B0); BAR;
;     LDB(B1, 1, 1); WAIT_V(0); BAR; WAIT_L(0); MMA(0, 1, At, B1); BAR;
;     LDA(At, 1, 1); BAR; WAIT_L(0); MMA(1, 0, At, B0); MMA(1, 1, At, B1); BAR; }
.Lwdma_skip_last:
	s_waitcnt lgkmcnt(8)
	s_barrier
	s_waitcnt lgkmcnt(0)
	s_setprio 1
	s_waitcnt lgkmcnt(0)
	v_mfma_f32_16x16x32_bf16 v[124:127], v[156:159], v[192:195], v[124:127]
	v_mfma_f32_16x16x32_bf16 v[120:123], v[184:187], v[192:195], v[120:123]
	v_mfma_f32_16x16x32_bf16 v[116:119], v[156:159], v[200:203], v[116:119]
	v_mfma_f32_16x16x32_bf16 v[112:115], v[184:187], v[200:203], v[112:115]
	v_mfma_f32_16x16x32_bf16 v[108:111], v[156:159], v[208:211], v[108:111]
	v_mfma_f32_16x16x32_bf16 v[104:107], v[184:187], v[208:211], v[104:107]
	v_mfma_f32_16x16x32_bf16 v[100:103], v[156:159], v[216:219], v[100:103]
	v_mfma_f32_16x16x32_bf16 v[96:99], v[184:187], v[216:219], v[96:99]
	v_mfma_f32_16x16x32_bf16 v[124:127], v[180:183], v[196:199], v[124:127]
	v_mfma_f32_16x16x32_bf16 v[120:123], v[188:191], v[196:199], v[120:123]
	v_mfma_f32_16x16x32_bf16 v[116:119], v[180:183], v[204:207], v[116:119]
	v_mfma_f32_16x16x32_bf16 v[112:115], v[188:191], v[204:207], v[112:115]
	v_mfma_f32_16x16x32_bf16 v[108:111], v[180:183], v[212:215], v[108:111]
	v_mfma_f32_16x16x32_bf16 v[104:107], v[188:191], v[212:215], v[104:107]
	v_mfma_f32_16x16x32_bf16 v[100:103], v[180:183], v[220:223], v[100:103]
	v_mfma_f32_16x16x32_bf16 v[96:99], v[188:191], v[220:223], v[96:99]
	s_setprio 0
	s_barrier
	s_mov_b32 m0, s4
	ds_read_b128 v[132:135], v150
	ds_read_b128 v[224:227], v150 offset:1024
	ds_read_b128 v[228:231], v150 offset:256
	ds_read_b128 v[232:235], v150 offset:1280
	global_load_lds_dwordx4 v[136:137], off
	s_mov_b32 m0, s5
	v_lshl_add_u64 v[240:241], v[136:137], 0, s[8:9]
	global_load_lds_dwordx4 v[138:139], off
	v_lshl_add_u64 v[242:243], v[138:139], 0, s[8:9]
	s_barrier
	s_waitcnt lgkmcnt(0)
	s_setprio 1
	s_waitcnt lgkmcnt(0)
	v_mfma_f32_16x16x32_bf16 v[84:87], v[132:135], v[192:195], v[84:87]
	v_mfma_f32_16x16x32_bf16 v[68:71], v[228:231], v[192:195], v[68:71]
	v_mfma_f32_16x16x32_bf16 v[52:55], v[132:135], v[200:203], v[52:55]
	v_mfma_f32_16x16x32_bf16 v[48:51], v[228:231], v[200:203], v[48:51]
	v_mfma_f32_16x16x32_bf16 v[44:47], v[132:135], v[208:211], v[44:47]
	v_mfma_f32_16x16x32_bf16 v[40:43], v[228:231], v[208:211], v[40:43]
	v_mfma_f32_16x16x32_bf16 v[36:39], v[132:135], v[216:219], v[36:39]
	v_mfma_f32_16x16x32_bf16 v[32:35], v[228:231], v[216:219], v[32:35]
	v_mfma_f32_16x16x32_bf16 v[84:87], v[224:227], v[196:199], v[84:87]
	v_mfma_f32_16x16x32_bf16 v[68:71], v[232:235], v[196:199], v[68:71]
	v_mfma_f32_16x16x32_bf16 v[52:55], v[224:227], v[204:207], v[52:55]
	v_mfma_f32_16x16x32_bf16 v[48:51], v[232:235], v[204:207], v[48:51]
	v_mfma_f32_16x16x32_bf16 v[44:47], v[224:227], v[212:215], v[44:47]
	v_mfma_f32_16x16x32_bf16 v[40:43], v[232:235], v[212:215], v[40:43]
	v_mfma_f32_16x16x32_bf16 v[36:39], v[224:227], v[220:223], v[36:39]
	v_mfma_f32_16x16x32_bf16 v[32:35], v[232:235], v[220:223], v[32:35]
	s_setprio 0
	s_mov_b32 m0, s1
	s_barrier
	ds_read_b128 v[136:139], v128 offset:16384
	ds_read_b128 v[192:195], v128 offset:17408
	ds_read_b128 v[196:199], v153 offset:16384
	ds_read_b128 v[200:203], v153 offset:17408
	ds_read_b128 v[204:207], v154 offset:16384
	ds_read_b128 v[208:211], v154 offset:17408
	ds_read_b128 v[212:215], v155 offset:16384
	ds_read_b128 v[216:219], v155 offset:17408
	global_load_lds_dwordx4 v[140:141], off
	s_mov_b32 m0, s6
	v_lshl_add_u64 v[244:245], v[140:141], 0, s[8:9]
	global_load_lds_dwordx4 v[142:143], off
	v_lshl_add_u64 v[246:247], v[142:143], 0, s[8:9]
	s_barrier
	s_waitcnt lgkmcnt(0)
	s_setprio 1
	s_waitcnt lgkmcnt(0)
	v_mfma_f32_16x16x32_bf16 v[28:31], v[156:159], v[136:139], v[28:31]
	v_mfma_f32_16x16x32_bf16 v[24:27], v[184:187], v[136:139], v[24:27]
	v_mfma_f32_16x16x32_bf16 v[20:23], v[156:159], v[196:199], v[20:23]
	v_mfma_f32_16x16x32_bf16 v[16:19], v[184:187], v[196:199], v[16:19]
	v_mfma_f32_16x16x32_bf16 v[12:15], v[156:159], v[204:207], v[12:15]
	v_mfma_f32_16x16x32_bf16 v[8:11], v[184:187], v[204:207], v[8:11]
	v_mfma_f32_16x16x32_bf16 v[4:7], v[156:159], v[212:215], v[4:7]
	v_mfma_f32_16x16x32_bf16 v[0:3], v[184:187], v[212:215], v[0:3]
	v_mfma_f32_16x16x32_bf16 v[28:31], v[180:183], v[192:195], v[28:31]
	v_mfma_f32_16x16x32_bf16 v[24:27], v[188:191], v[192:195], v[24:27]
	v_mfma_f32_16x16x32_bf16 v[20:23], v[180:183], v[200:203], v[20:23]
	v_mfma_f32_16x16x32_bf16 v[16:19], v[188:191], v[200:203], v[16:19]
	v_mfma_f32_16x16x32_bf16 v[12:15], v[180:183], v[208:211], v[12:15]
	v_mfma_f32_16x16x32_bf16 v[8:11], v[188:191], v[208:211], v[8:11]
	v_mfma_f32_16x16x32_bf16 v[4:7], v[180:183], v[216:219], v[4:7]
	v_mfma_f32_16x16x32_bf16 v[0:3], v[188:191], v[216:219], v[0:3]
	s_setprio 0
	s_barrier
	s_mov_b32 m0, s7
	v_lshl_add_u64 v[248:249], v[144:145], 0, s[8:9]
	global_load_lds_dwordx4 v[144:145], off
	s_mov_b32 m0, s35
	v_lshl_add_u64 v[250:251], v[146:147], 0, s[8:9]
	global_load_lds_dwordx4 v[146:147], off
	s_waitcnt vmcnt(6)
	s_barrier
	s_setprio 1
	v_mfma_f32_16x16x32_bf16 v[56:59], v[132:135], v[136:139], v[56:59]
	v_mfma_f32_16x16x32_bf16 v[60:63], v[228:231], v[136:139], v[60:63]
	v_mfma_f32_16x16x32_bf16 v[64:67], v[132:135], v[196:199], v[64:67]
	v_mfma_f32_16x16x32_bf16 v[72:75], v[228:231], v[196:199], v[72:75]
	v_mfma_f32_16x16x32_bf16 v[76:79], v[132:135], v[204:207], v[76:79]
	v_mfma_f32_16x16x32_bf16 v[80:83], v[228:231], v[204:207], v[80:83]
	v_mfma_f32_16x16x32_bf16 v[88:91], v[132:135], v[212:215], v[88:91]
	v_mfma_f32_16x16x32_bf16 v[92:95], v[228:231], v[212:215], v[92:95]
	v_mfma_f32_16x16x32_bf16 v[56:59], v[224:227], v[192:195], v[56:59]
	v_mfma_f32_16x16x32_bf16 v[60:63], v[232:235], v[192:195], v[60:63]
	v_mfma_f32_16x16x32_bf16 v[64:67], v[224:227], v[200:203], v[64:67]
	v_mfma_f32_16x16x32_bf16 v[72:75], v[232:235], v[200:203], v[72:75]
	v_mfma_f32_16x16x32_bf16 v[76:79], v[224:227], v[208:211], v[76:79]
	v_mfma_f32_16x16x32_bf16 v[80:83], v[232:235], v[208:211], v[80:83]
	v_mfma_f32_16x16x32_bf16 v[88:91], v[224:227], v[216:219], v[88:91]
	v_mfma_f32_16x16x32_bf16 v[92:95], v[232:235], v[216:219], v[92:95]
	s_setprio 0
	s_barrier
; #define LDA(dst, b, h) _Pragma("unroll") for (int m = 0; m < 4; ++m) _Pragma("unroll") for (int k = 0; k < 2; ++k) \
;     dst[m][k] = *(const bf16x8*)((const unsigned char*)SA(b, h) + lds_byte1(wr * 64 + m * 16 + fr, k * 32 + fq * 8))
; #define LDB(dst, b, h) _Pragma("unroll") for (int n = 0; n < 2; ++n) _Pragma("unroll") for (int k = 0; k < 2; ++k) \
;     dst[n][k] = *(const bf16x8*)((const unsigned char*)SB(b, h) + lds_byte1(wc * 32 + n * 16 + fr, k * 32 + fq * 8))
; #define MMA(ai, bj, At_, Bt_) do { __builtin_amdgcn_s_setprio(1); \
;     _Pragma("unroll") for (int m = 0; m < 4; ++m) _Pragma("unroll") for (int n = 0; n < 2; ++n) _Pragma("unroll") for (int k = 0; k < 2; ++k) \
;       acc[ai][bj][m][n] = mfma16(At_[m][k], Bt_[n][k], acc[ai][bj][m][n]); \
;     __builtin_amdgcn_s_setprio(0); } while (0)
; #define WAIT_V(n) asm volatile("s_waitcnt vmcnt(" #n ")" ::: "memory")
; #define WAIT_L(n) asm volatile("s_waitcnt lgkmcnt(" #n ")" ::: "memory")
; #define BAR __builtin_amdgcn_s_barrier()
; DEV void gemm_tile(const u16* __restrict__ A, const u16* __restrict__ Bt, u16* __restrict__ C, int N, int K,
;                    int brow, int bcol, unsigned char* smem, int epi, const GateEpi& ge) {
;     ...
;     LDB(B1, 0, 1); BAR; WAIT_L(0); MMA(0, 1, At, B1); BAR;
;     LDA(At, 0, 1); WAIT_V(4); BAR; WAIT_L(0); MMA(1, 0, At, B0); MMA(1, 1, At, B1); BAR; }
;   { LDB(B0, 1, 0); LDA(At, 1, 0); WAIT_V(2); BAR; WAIT_L(0); MMA(0, 0, At, B0); BAR;
;     ...
;   u16* Cw = C + (size_t)(brow + wr * 64) * N + bcol + wc * 32;
; #pragma unroll
;   for (int ai = 0; ai < 2; ++ai)
; #pragma unroll
;     for (int bj = 0; bj < 2; ++bj)
; #pragma unroll
;       for (int m = 0; m < 4; ++m)
; #pragma unroll
;         for (int n = 0; n < 2; ++n)
; #pragma unroll
;           for (int j = 0; j < 4; ++j)
;             Cw[(size_t)(ai * 128 + m * 16 + fq2 * 4 + j) * N + (bj * 128 + n * 16 + fr2)] = f2bf(acc[ai][bj][m][n][j]);
	ds_read_b128 v[144:147], v149
	ds_read_b128 v[156:159], v149 offset:1024
	ds_read_b128 v[180:183], v149 offset:256
	ds_read_b128 v[184:187], v149 offset:1280
	s_mov_b32 m0, s41
	ds_read_b128 v[140:143], v128 offset:32768
	ds_read_b128 v[188:191], v128 offset:33792
	ds_read_b128 v[192:195], v153 offset:32768
	ds_read_b128 v[196:199], v153 offset:33792
	ds_read_b128 v[200:203], v154 offset:32768
	ds_read_b128 v[204:207], v154 offset:33792
	ds_read_b128 v[208:211], v155 offset:32768
	ds_read_b128 v[212:215], v155 offset:33792
	global_load_lds_dwordx4 v[236:237], off
	s_mov_b32 m0, vcc_lo
	v_lshl_add_u64 v[132:133], v[236:237], 0, s[8:9]
	global_load_lds_dwordx4 v[238:239], off
	v_lshl_add_u64 v[134:135], v[238:239], 0, s[8:9]
	s_waitcnt lgkmcnt(8)
	s_barrier
	s_waitcnt lgkmcnt(0)
	s_setprio 1
	s_waitcnt lgkmcnt(0)
	v_mfma_f32_16x16x32_bf16 v[124:127], v[144:147], v[140:143], v[124:127]
	v_mfma_f32_16x16x32_bf16 v[120:123], v[180:183], v[140:143], v[120:123]
	v_mfma_f32_16x16x32_bf16 v[116:119], v[144:147], v[192:195], v[116:119]
	v_mfma_f32_16x16x32_bf16 v[112:115], v[180:183], v[192:195], v[112:115]
	v_mfma_f32_16x16x32_bf16 v[108:111], v[144:147], v[200:203], v[108:111]
	v_mfma_f32_16x16x32_bf16 v[104:107], v[180:183], v[200:203], v[104:107]
	v_mfma_f32_16x16x32_bf16 v[100:103], v[144:147], v[208:211], v[100:103]
	v_mfma_f32_16x16x32_bf16 v[96:99], v[180:183], v[208:211], v[96:99]
	v_mfma_f32_16x16x32_bf16 v[124:127], v[156:159], v[188:191], v[124:127]
	v_mfma_f32_16x16x32_bf16 v[120:123], v[184:187], v[188:191], v[120:123]
	v_mfma_f32_16x16x32_bf16 v[116:119], v[156:159], v[196:199], v[116:119]
	v_mfma_f32_16x16x32_bf16 v[112:115], v[184:187], v[196:199], v[112:115]
	v_mfma_f32_16x16x32_bf16 v[108:111], v[156:159], v[204:207], v[108:111]
	v_mfma_f32_16x16x32_bf16 v[104:107], v[184:187], v[204:207], v[104:107]
	v_mfma_f32_16x16x32_bf16 v[100:103], v[156:159], v[212:215], v[100:103]
	v_mfma_f32_16x16x32_bf16 v[96:99], v[184:187], v[212:215], v[96:99]
	s_setprio 0
	s_barrier
	s_mov_b32 m0, vcc_hi
	ds_read_b128 v[216:219], v148
	ds_read_b128 v[220:223], v148 offset:1024
	ds_read_b128 v[224:227], v148 offset:256
	ds_read_b128 v[228:231], v148 offset:1280
	global_load_lds_dwordx4 v[240:241], off
	s_mov_b32 m0, s28
	v_lshl_add_u64 v[136:137], v[240:241], 0, s[8:9]
	global_load_lds_dwordx4 v[242:243], off
	v_lshl_add_u64 v[138:139], v[242:243], 0, s[8:9]
	s_andn2_b64 s[54:55], exec, s[2:3]
	s_cmp_lg_u64 s[54:55], 0
	s_cbranch_scc0 .Lq_skip_q00
	s_add_i32 s53, s51, s49
	s_mul_hi_u32 s59, s53, s44
	s_mul_i32 s58, s53, s44
	s_lshl_b64 s[58:59], s[58:59], 1
	s_add_u32 s58, s14, s58
	s_addc_u32 s59, s15, s59
	s_lshl_b64 s[54:55], s[92:93], 1
	s_add_u32 s58, s58, s54
	s_addc_u32 s59, s59, s55
	s_lshl_b32 s54, s50, 6
	s_add_u32 s58, s58, s54
	s_addc_u32 s59, s59, 0
	s_lshl_b32 s0, s44, 5
	v_readfirstlane_b32 s53, v160
	s_andn2_b32 s53, s53, 63
	s_nop 0
	v_or_b32_e32 v237, s53, v161
	v_bfe_u32 v238, v237, 4, 2
	v_and_b32_e32 v237, 15, v237
	v_mul_u32_u24_e32 v236, s44, v237
	v_lshlrev_b32_e32 v236, 1, v236
	v_lshl_add_u32 v236, v238, 4, v236
	v_cvt_pk_bf16_f32 v240, v124, v125
	v_cvt_pk_bf16_f32 v241, v126, v127
	v_cvt_pk_bf16_f32 v242, v120, v121
	v_cvt_pk_bf16_f32 v243, v122, v123
	global_store_dwordx4 v236, v[240:243], s[58:59]
	s_add_u32 s58, s58, s0
	s_addc_u32 s59, s59, 0
	s_nop 1
	v_cvt_pk_bf16_f32 v240, v116, v117
	v_cvt_pk_bf16_f32 v241, v118, v119
	v_cvt_pk_bf16_f32 v242, v112, v113
	v_cvt_pk_bf16_f32 v243, v114, v115
	global_store_dwordx4 v236, v[240:243], s[58:59]
	s_add_u32 s58, s58, s0
	s_addc_u32 s59, s59, 0
	s_nop 1
	v_cvt_pk_bf16_f32 v240, v108, v109
	v_cvt_pk_bf16_f32 v241, v110, v111
	v_cvt_pk_bf16_f32 v242, v104, v105
	v_cvt_pk_bf16_f32 v243, v106, v107
	global_store_dwordx4 v236, v[240:243], s[58:59]
	s_add_u32 s58, s58, s0
	s_addc_u32 s59, s59, 0
	s_nop 1
	v_cvt_pk_bf16_f32 v240, v100, v101
	v_cvt_pk_bf16_f32 v241, v102, v103
	v_cvt_pk_bf16_f32 v242, v96, v97
	v_cvt_pk_bf16_f32 v243, v98, v99
	global_store_dwordx4 v236, v[240:243], s[58:59]
	s_add_u32 s58, s58, s0
	s_addc_u32 s59, s59, 0
	s_nop 1
.Lq_skip_q00:
	s_barrier
	s_waitcnt lgkmcnt(0)
	s_setprio 1
	s_waitcnt lgkmcnt(0)
	v_mfma_f32_16x16x32_bf16 v[84:87], v[216:219], v[140:143], v[84:87]
	v_mfma_f32_16x16x32_bf16 v[68:71], v[224:227], v[140:143], v[68:71]
	v_mfma_f32_16x16x32_bf16 v[52:55], v[216:219], v[192:195], v[52:55]
	v_mfma_f32_16x16x32_bf16 v[48:51], v[224:227], v[192:195], v[48:51]
	v_mfma_f32_16x16x32_bf16 v[44:47], v[216:219], v[200:203], v[44:47]
	v_mfma_f32_16x16x32_bf16 v[40:43], v[224:227], v[200:203], v[40:43]
	v_mfma_f32_16x16x32_bf16 v[36:39], v[216:219], v[208:211], v[36:39]
	v_mfma_f32_16x16x32_bf16 v[32:35], v[224:227], v[208:211], v[32:35]
	v_mfma_f32_16x16x32_bf16 v[84:87], v[220:223], v[188:191], v[84:87]
	v_mfma_f32_16x16x32_bf16 v[68:71], v[228:231], v[188:191], v[68:71]
	v_mfma_f32_16x16x32_bf16 v[52:55], v[220:223], v[196:199], v[52:55]
	v_mfma_f32_16x16x32_bf16 v[48:51], v[228:231], v[196:199], v[48:51]
	v_mfma_f32_16x16x32_bf16 v[44:47], v[220:223], v[204:207], v[44:47]
	v_mfma_f32_16x16x32_bf16 v[40:43], v[228:231], v[204:207], v[40:43]
	v_mfma_f32_16x16x32_bf16 v[36:39], v[220:223], v[212:215], v[36:39]
	v_mfma_f32_16x16x32_bf16 v[32:35], v[228:231], v[212:215], v[32:35]
	s_setprio 0
	s_mov_b32 m0, s94
	s_barrier
	ds_read_b128 v[188:191], v128 offset:49152
	ds_read_b128 v[192:195], v128 offset:50176
	ds_read_b128 v[196:199], v153 offset:49152
	ds_read_b128 v[200:203], v153 offset:50176
	ds_read_b128 v[204:207], v154 offset:49152
	ds_read_b128 v[208:211], v154 offset:50176
	ds_read_b128 v[212:215], v155 offset:49152
	ds_read_b128 v[232:235], v155 offset:50176
	global_load_lds_dwordx4 v[244:245], off
	s_mov_b32 m0, s95
	v_lshl_add_u64 v[140:141], v[244:245], 0, s[8:9]
	global_load_lds_dwordx4 v[246:247], off
	v_lshl_add_u64 v[142:143], v[246:247], 0, s[8:9]
	s_andn2_b64 s[54:55], exec, s[2:3]
	s_cmp_lg_u64 s[54:55], 0
	s_cbranch_scc0 .Lq_skip_q01
	s_lshl_b32 s54, s0, 2
	s_sub_u32 s58, s58, s54
	s_subb_u32 s59, s59, 0
	v_cvt_pk_bf16_f32 v240, v84, v85
	v_cvt_pk_bf16_f32 v241, v86, v87
	v_cvt_pk_bf16_f32 v242, v68, v69
	v_cvt_pk_bf16_f32 v243, v70, v71
	global_store_dwordx4 v236, v[240:243], s[58:59] offset:256
	s_add_u32 s58, s58, s0
	s_addc_u32 s59, s59, 0
	v_cvt_pk_bf16_f32 v244, v52, v53
	v_cvt_pk_bf16_f32 v245, v54, v55
	v_cvt_pk_bf16_f32 v246, v48, v49
	v_cvt_pk_bf16_f32 v247, v50, v51
	global_store_dwordx4 v236, v[244:247], s[58:59] offset:256
	s_add_u32 s58, s58, s0
	s_addc_u32 s59, s59, 0
	v_cvt_pk_bf16_f32 v240, v44, v45
	v_cvt_pk_bf16_f32 v241, v46, v47
	v_cvt_pk_bf16_f32 v242, v40, v41
	v_cvt_pk_bf16_f32 v243, v42, v43
	global_store_dwordx4 v236, v[240:243], s[58:59] offset:256
	s_add_u32 s58, s58, s0
	s_addc_u32 s59, s59, 0
	v_cvt_pk_bf16_f32 v244, v36, v37
	v_cvt_pk_bf16_f32 v245, v38, v39
	v_cvt_pk_bf16_f32 v246, v32, v33
	v_cvt_pk_bf16_f32 v247, v34, v35
	global_store_dwordx4 v236, v[244:247], s[58:59] offset:256
	s_add_u32 s58, s58, s0
	s_addc_u32 s59, s59, 0
; #define LDA(dst, b, h) _Pragma("unroll") for (int m = 0; m < 4; ++m) _Pragma("unroll") for (int k = 0; k < 2; ++k) \
;     dst[m][k] = *(const bf16x8*)((const unsigned char*)SA(b, h) + lds_byte1(wr * 64 + m * 16 + fr, k * 32 + fq * 8))
; #define LDB(dst, b, h) _Pragma("unroll") for (int n = 0; n < 2; ++n) _Pragma("unroll") for (int k = 0; k < 2; ++k) \
;     dst[n][k] = *(const bf16x8*)((const unsigned char*)SB(b, h) + lds_byte1(wc * 32 + n * 16 + fr, k * 32 + fq * 8))
; #define MMA(ai, bj, At_, Bt_) do { __builtin_amdgcn_s_setprio(1); \
;     _Pragma("unroll") for (int m = 0; m < 4; ++m) _Pragma("unroll") for (int n = 0; n < 2; ++n) _Pragma("unroll") for (int k = 0; k < 2; ++k) \
;       acc[ai][bj][m][n] = mfma16(At_[m][k], Bt_[n][k], acc[ai][bj][m][n]); \
;     __builtin_amdgcn_s_setprio(0); } while (0)
; #define WAIT_V(n) asm volatile("s_waitcnt vmcnt(" #n ")" ::: "memory")
; #define WAIT_L(n) asm volatile("s_waitcnt lgkmcnt(" #n ")" ::: "memory")
; #define BAR __builtin_amdgcn_s_barrier()
; DEV void gemm_tile(const u16* __restrict__ A, const u16* __restrict__ Bt, u16* __restrict__ C, int N, int K,
;                    int brow, int bcol, unsigned char* smem, int epi, const GateEpi& ge) {
;     ...
;   { LDB(B0, 1, 0); LDA(At, 1, 0); WAIT_V(2); BAR; WAIT_L(0); MMA(0, 0, At, B0); BAR;
;     LDB(B1, 1, 1); WAIT_V(0); BAR; WAIT_L(0); MMA(0, 1, At, B1); BAR;
;     LDA(At, 1, 1); BAR; WAIT_L(0); MMA(1, 0, At, B0); MMA(1, 1, At, B1); BAR; }
;     ...
;   u16* Cw = C + (size_t)(brow + wr * 64) * N + bcol + wc * 32;
; #pragma unroll
;   for (int ai = 0; ai < 2; ++ai)
; #pragma unroll
;     for (int bj = 0; bj < 2; ++bj)
; #pragma unroll
;       for (int m = 0; m < 4; ++m)
; #pragma unroll
;         for (int n = 0; n < 2; ++n)
; #pragma unroll
;           for (int j = 0; j < 4; ++j)
;             Cw[(size_t)(ai * 128 + m * 16 + fq2 * 4 + j) * N + (bj * 128 + n * 16 + fr2)] = f2bf(acc[ai][bj][m][n][j]);
.Lq_skip_q01:
	s_barrier
	s_waitcnt lgkmcnt(0)
	s_setprio 1
	s_waitcnt lgkmcnt(0)
	v_mfma_f32_16x16x32_bf16 v[28:31], v[144:147], v[188:191], v[28:31]
	v_mfma_f32_16x16x32_bf16 v[24:27], v[180:183], v[188:191], v[24:27]
	v_mfma_f32_16x16x32_bf16 v[20:23], v[144:147], v[196:199], v[20:23]
	v_mfma_f32_16x16x32_bf16 v[16:19], v[180:183], v[196:199], v[16:19]
	v_mfma_f32_16x16x32_bf16 v[12:15], v[144:147], v[204:207], v[12:15]
	v_mfma_f32_16x16x32_bf16 v[8:11], v[180:183], v[204:207], v[8:11]
	v_mfma_f32_16x16x32_bf16 v[4:7], v[144:147], v[212:215], v[4:7]
	v_mfma_f32_16x16x32_bf16 v[0:3], v[180:183], v[212:215], v[0:3]
	v_mfma_f32_16x16x32_bf16 v[28:31], v[156:159], v[192:195], v[28:31]
	v_mfma_f32_16x16x32_bf16 v[24:27], v[184:187], v[192:195], v[24:27]
	v_mfma_f32_16x16x32_bf16 v[20:23], v[156:159], v[200:203], v[20:23]
	v_mfma_f32_16x16x32_bf16 v[16:19], v[184:187], v[200:203], v[16:19]
	v_mfma_f32_16x16x32_bf16 v[12:15], v[156:159], v[208:211], v[12:15]
	v_mfma_f32_16x16x32_bf16 v[8:11], v[184:187], v[208:211], v[8:11]
	v_mfma_f32_16x16x32_bf16 v[4:7], v[156:159], v[232:235], v[4:7]
	v_mfma_f32_16x16x32_bf16 v[0:3], v[184:187], v[232:235], v[0:3]
	s_setprio 0
	s_barrier
	s_mov_b32 m0, s62
	v_lshl_add_u64 v[144:145], v[248:249], 0, s[8:9]
	global_load_lds_dwordx4 v[248:249], off
	s_mov_b32 m0, s63
	v_lshl_add_u64 v[146:147], v[250:251], 0, s[8:9]
	global_load_lds_dwordx4 v[250:251], off
	s_andn2_b64 s[54:55], exec, s[2:3]
	s_cmp_lg_u64 s[54:55], 0
	s_cbranch_scc0 .Lq_skip_q10
	s_lshl_b32 s54, s0, 2
	s_add_u32 s58, s58, s54
	s_addc_u32 s59, s59, 0
	v_cvt_pk_bf16_f32 v240, v28, v29
	v_cvt_pk_bf16_f32 v241, v30, v31
	v_cvt_pk_bf16_f32 v242, v24, v25
	v_cvt_pk_bf16_f32 v243, v26, v27
	global_store_dwordx4 v236, v[240:243], s[58:59]
	s_add_u32 s58, s58, s0
	s_addc_u32 s59, s59, 0
	v_cvt_pk_bf16_f32 v244, v20, v21
	v_cvt_pk_bf16_f32 v245, v22, v23
	v_cvt_pk_bf16_f32 v246, v16, v17
	v_cvt_pk_bf16_f32 v247, v18, v19
	global_store_dwordx4 v236, v[244:247], s[58:59]
	s_add_u32 s58, s58, s0
	s_addc_u32 s59, s59, 0
	v_cvt_pk_bf16_f32 v240, v12, v13
	v_cvt_pk_bf16_f32 v241, v14, v15
	v_cvt_pk_bf16_f32 v242, v8, v9
	v_cvt_pk_bf16_f32 v243, v10, v11
	global_store_dwordx4 v236, v[240:243], s[58:59]
	s_add_u32 s58, s58, s0
	s_addc_u32 s59, s59, 0
	v_cvt_pk_bf16_f32 v244, v4, v5
	v_cvt_pk_bf16_f32 v245, v6, v7
	v_cvt_pk_bf16_f32 v246, v0, v1
	v_cvt_pk_bf16_f32 v247, v2, v3
	global_store_dwordx4 v236, v[244:247], s[58:59]
	s_add_u32 s58, s58, s0
	s_addc_u32 s59, s59, 0
.Lq_skip_q10:
	s_andn2_b64 s[54:55], exec, s[2:3]
	s_cmp_lg_u64 s[54:55], 0
	s_cbranch_scc1 .Ll_plainw
	s_waitcnt vmcnt(6)
	s_branch .Ll_wdone
.Ll_plainw:
	s_waitcnt vmcnt(18)
.Ll_wdone:
	s_barrier
	s_setprio 1
	v_mfma_f32_16x16x32_bf16 v[56:59], v[216:219], v[188:191], v[56:59]
	v_mfma_f32_16x16x32_bf16 v[60:63], v[224:227], v[188:191], v[60:63]
	v_mfma_f32_16x16x32_bf16 v[64:67], v[216:219], v[196:199], v[64:67]
	v_mfma_f32_16x16x32_bf16 v[72:75], v[224:227], v[196:199], v[72:75]
	v_mfma_f32_16x16x32_bf16 v[76:79], v[216:219], v[204:207], v[76:79]
	v_mfma_f32_16x16x32_bf16 v[80:83], v[224:227], v[204:207], v[80:83]
	v_mfma_f32_16x16x32_bf16 v[88:91], v[216:219], v[212:215], v[88:91]
	v_mfma_f32_16x16x32_bf16 v[92:95], v[224:227], v[212:215], v[92:95]
	v_mfma_f32_16x16x32_bf16 v[56:59], v[220:223], v[192:195], v[56:59]
	v_mfma_f32_16x16x32_bf16 v[60:63], v[228:231], v[192:195], v[60:63]
	v_mfma_f32_16x16x32_bf16 v[64:67], v[220:223], v[200:203], v[64:67]
	v_mfma_f32_16x16x32_bf16 v[72:75], v[228:231], v[200:203], v[72:75]
	v_mfma_f32_16x16x32_bf16 v[76:79], v[220:223], v[208:211], v[76:79]
	v_mfma_f32_16x16x32_bf16 v[80:83], v[228:231], v[208:211], v[80:83]
	v_mfma_f32_16x16x32_bf16 v[88:91], v[220:223], v[232:235], v[88:91]
	v_mfma_f32_16x16x32_bf16 v[92:95], v[228:231], v[232:235], v[92:95]
	s_setprio 0
	s_barrier
	s_mov_b32 m0, s56
	s_nop 0
	global_load_lds_dwordx4 v[132:133], off
	s_mov_b32 m0, s52
	s_nop 0
	global_load_lds_dwordx4 v[134:135], off
	s_andn2_b64 s[54:55], exec, s[2:3]
	s_cmp_lg_u64 s[54:55], 0
	s_cbranch_scc0 .Lq_skip_q11
	s_lshl_b32 s54, s0, 2
	s_sub_u32 s58, s58, s54
	s_subb_u32 s59, s59, 0
	v_cvt_pk_bf16_f32 v240, v56, v57
	v_cvt_pk_bf16_f32 v241, v58, v59
	v_cvt_pk_bf16_f32 v242, v60, v61
	v_cvt_pk_bf16_f32 v243, v62, v63
	global_store_dwordx4 v236, v[240:243], s[58:59] offset:256
	s_add_u32 s58, s58, s0
	s_addc_u32 s59, s59, 0
	v_cvt_pk_bf16_f32 v244, v64, v65
	v_cvt_pk_bf16_f32 v245, v66, v67
	v_cvt_pk_bf16_f32 v246, v72, v73
	v_cvt_pk_bf16_f32 v247, v74, v75
	global_store_dwordx4 v236, v[244:247], s[58:59] offset:256
	s_add_u32 s58, s58, s0
	s_addc_u32 s59, s59, 0
	v_cvt_pk_bf16_f32 v240, v76, v77
	v_cvt_pk_bf16_f32 v241, v78, v79
	v_cvt_pk_bf16_f32 v242, v80, v81
	v_cvt_pk_bf16_f32 v243, v82, v83
	global_store_dwordx4 v236, v[240:243], s[58:59] offset:256
	s_add_u32 s58, s58, s0
	s_addc_u32 s59, s59, 0
	v_cvt_pk_bf16_f32 v244, v88, v89
	v_cvt_pk_bf16_f32 v245, v90, v91
	v_cvt_pk_bf16_f32 v246, v92, v93
	v_cvt_pk_bf16_f32 v247, v94, v95
	global_store_dwordx4 v236, v[244:247], s[58:59] offset:256
	s_add_u32 s58, s58, s0
	s_addc_u32 s59, s59, 0
.Lq_skip_q11:
	s_mov_b32 s63, 1

; #define MMA(ai, bj, At_, Bt_) do { __builtin_amdgcn_s_setprio(1); \
;     _Pragma("unroll") for (int m = 0; m < 4; ++m) _Pragma("unroll") for (int n = 0; n < 2; ++n) _Pragma("unroll") for (int k = 0; k < 2; ++k) \
;       acc[ai][bj][m][n] = mfma16(At_[m][k], Bt_[n][k], acc[ai][bj][m][n]); \
;     __builtin_amdgcn_s_setprio(0); } while (0)
; #define WAIT_V(n) asm volatile("s_waitcnt vmcnt(" #n ")" ::: "memory")
; #define BAR __builtin_amdgcn_s_barrier()
; DEV void gemm_tile(const u16* __restrict__ A, const u16* __restrict__ Bt, u16* __restrict__ C, int N, int K,
;                    int brow, int bcol, unsigned char* smem, int epi, const GateEpi& ge) {
;     ...
;     WAIT_V(6); BAR; MMA(1, 1, At, B1); BAR;
.Lf_plainw:
	s_waitcnt vmcnt(10)
